# GEMM mainloops: compiler-inserted vmcnt(0) between LDS-DMA issue and ds_read replaced by s_nop (loads now overlap the MFMAs)
# speedup vs baseline: 1.0463x; 1.0463x over previous
; template <bool DB, class AF>
; DEVI void gemm_mainloop(int tid, u16* sA, u16* sB, AF af, const u16* __restrict__ Bt, int ldb, int m0, int n0, int nk,
;                         f32x4 (&acc)[4][4]) {
;     ...
;     STAGE_(0, 0)
; #pragma unroll 1
;     for (int kt = 0; kt < nk; kt += 2) {
;       asm volatile("s_waitcnt vmcnt(0)" ::: "memory");
;       __syncthreads();
;       { const int kk = (kt + 1) * 64; STAGE_(1, kk) }
;       COMPUTE_SW_(0)
;       asm volatile("s_waitcnt vmcnt(0)" ::: "memory");
;       __syncthreads();
;       if (kt + 2 < nk) { const int kk = (kt + 2) * 64; STAGE_(0, kk) }
;       COMPUTE_SW_(1)
.LBB0_258:
	s_nop 0
	ds_read_b128 v[82:85], v123 offset:32768
	ds_read_b128 v[86:89], v123 offset:34816
	ds_read_b128 v[90:93], v123 offset:36864
	ds_read_b128 v[94:97], v123 offset:38912
	ds_read_b128 v[128:131], v124 offset:49152
	ds_read_b128 v[132:135], v124 offset:51200
	ds_read_b128 v[136:139], v124 offset:53248
	ds_read_b128 v[140:143], v124 offset:55296
	s_add_i32 s9, s9, 2
	s_setprio 1
	s_waitcnt lgkmcnt(0)
	v_mfma_f32_16x16x32_bf16 v[0:3], v[128:131], v[82:85], v[0:3]
	v_mfma_f32_16x16x32_bf16 v[4:7], v[128:131], v[86:89], v[4:7]
	v_mfma_f32_16x16x32_bf16 v[8:11], v[128:131], v[90:93], v[8:11]
	v_mfma_f32_16x16x32_bf16 v[12:15], v[128:131], v[94:97], v[12:15]
	v_mfma_f32_16x16x32_bf16 v[16:19], v[132:135], v[82:85], v[16:19]
	v_mfma_f32_16x16x32_bf16 v[20:23], v[132:135], v[86:89], v[20:23]
	v_mfma_f32_16x16x32_bf16 v[24:27], v[132:135], v[90:93], v[24:27]
	v_mfma_f32_16x16x32_bf16 v[32:35], v[136:139], v[82:85], v[32:35]
	v_mfma_f32_16x16x32_bf16 v[36:39], v[136:139], v[86:89], v[36:39]
	v_mfma_f32_16x16x32_bf16 v[48:51], v[140:143], v[82:85], v[48:51]
	v_mfma_f32_16x16x32_bf16 v[128:131], v[132:135], v[94:97], v[28:31]
	v_mfma_f32_16x16x32_bf16 v[132:135], v[136:139], v[90:93], v[40:43]
	v_mfma_f32_16x16x32_bf16 v[136:139], v[136:139], v[94:97], v[44:47]
	v_mfma_f32_16x16x32_bf16 v[82:85], v[140:143], v[86:89], v[52:55]
	v_mfma_f32_16x16x32_bf16 v[86:89], v[140:143], v[90:93], v[56:59]
	v_mfma_f32_16x16x32_bf16 v[90:93], v[140:143], v[94:97], v[60:63]
	s_setprio 0
	ds_read_b128 v[94:97], v125 offset:32768
	ds_read_b128 v[140:143], v125 offset:34816
	ds_read_b128 v[144:147], v125 offset:36864
	ds_read_b128 v[148:151], v125 offset:38912
	ds_read_b128 v[40:43], v126 offset:49152
	ds_read_b128 v[52:55], v126 offset:51200
	ds_read_b128 v[152:155], v126 offset:53248
	ds_read_b128 v[156:159], v126 offset:55296
	s_setprio 1
	s_waitcnt lgkmcnt(3)
	v_mfma_f32_16x16x32_bf16 v[60:63], v[40:43], v[94:97], v[0:3]
	v_mfma_f32_16x16x32_bf16 v[44:47], v[40:43], v[140:143], v[4:7]
	v_mfma_f32_16x16x32_bf16 v[28:31], v[40:43], v[144:147], v[8:11]
	v_mfma_f32_16x16x32_bf16 v[12:15], v[40:43], v[148:151], v[12:15]
	s_waitcnt lgkmcnt(2)
	v_mfma_f32_16x16x32_bf16 v[56:59], v[52:55], v[94:97], v[16:19]
	v_mfma_f32_16x16x32_bf16 v[40:43], v[52:55], v[140:143], v[20:23]
	v_mfma_f32_16x16x32_bf16 v[24:27], v[52:55], v[144:147], v[24:27]
	v_mfma_f32_16x16x32_bf16 v[8:11], v[52:55], v[148:151], v[128:131]
	s_waitcnt lgkmcnt(1)
	v_mfma_f32_16x16x32_bf16 v[52:55], v[152:155], v[94:97], v[32:35]
	v_mfma_f32_16x16x32_bf16 v[36:39], v[152:155], v[140:143], v[36:39]
	v_mfma_f32_16x16x32_bf16 v[20:23], v[152:155], v[144:147], v[132:135]
	v_mfma_f32_16x16x32_bf16 v[4:7], v[152:155], v[148:151], v[136:139]
	s_waitcnt lgkmcnt(0)
	v_mfma_f32_16x16x32_bf16 v[48:51], v[156:159], v[94:97], v[48:51]
	v_mfma_f32_16x16x32_bf16 v[32:35], v[156:159], v[140:143], v[82:85]
	v_mfma_f32_16x16x32_bf16 v[16:19], v[156:159], v[144:147], v[86:89]
	v_mfma_f32_16x16x32_bf16 v[0:3], v[156:159], v[148:151], v[90:93]
	s_setprio 0
	v_lshl_add_u64 v[66:67], v[66:67], 0, s[20:21]
	v_lshl_add_u64 v[68:69], v[68:69], 0, s[20:21]
	v_lshl_add_u64 v[70:71], v[70:71], 0, s[20:21]
	v_lshl_add_u64 v[72:73], v[72:73], 0, s[20:21]
	v_lshl_add_u64 v[74:75], v[74:75], 0, s[20:21]
	v_lshl_add_u64 v[76:77], v[76:77], 0, s[20:21]
	v_lshl_add_u64 v[78:79], v[78:79], 0, s[20:21]
	s_andn2_b64 vcc, exec, s[4:5]
	v_lshl_add_u64 v[80:81], v[80:81], 0, s[20:21]
	s_cbranch_vccz .LBB0_261
; template <bool DB, class AF>
; DEVI void gemm_mainloop(int tid, u16* sA, u16* sB, AF af, const u16* __restrict__ Bt, int ldb, int m0, int n0, int nk,
;                         f32x4 (&acc)[4][4]) {
;     ...
;     STAGE_(0, 0)
; #pragma unroll 1
;     for (int kt = 0; kt < nk; kt += 2) {
;       asm volatile("s_waitcnt vmcnt(0)" ::: "memory");
;       __syncthreads();
;       { const int kk = (kt + 1) * 64; STAGE_(1, kk) }
;       COMPUTE_SW_(0)
;       asm volatile("s_waitcnt vmcnt(0)" ::: "memory");
;       __syncthreads();
;       if (kt + 2 < nk) { const int kk = (kt + 2) * 64; STAGE_(0, kk) }
;       COMPUTE_SW_(1)
.LBB0_259:
	v_lshl_add_u64 v[82:83], v[74:75], 0, v[64:65]
	v_readfirstlane_b32 s4, v115
	v_lshl_add_u64 v[84:85], v[82:83], 0, s[18:19]
	s_mov_b32 m0, s4
	s_waitcnt vmcnt(0)
	s_waitcnt vmcnt(0) lgkmcnt(0)
	s_barrier
	global_load_lds_dwordx4 v[84:85], off
	v_lshl_add_u64 v[84:85], v[66:67], 0, v[64:65]
	v_readfirstlane_b32 s4, v116
	v_lshl_add_u64 v[86:87], v[84:85], 0, s[18:19]
	s_mov_b32 m0, s4
	v_readfirstlane_b32 s4, v117
	global_load_lds_dwordx4 v[86:87], off
	v_lshl_add_u64 v[86:87], v[76:77], 0, v[64:65]
	v_lshl_add_u64 v[88:89], v[86:87], 0, s[18:19]
	s_mov_b32 m0, s4
	v_readfirstlane_b32 s4, v118
	global_load_lds_dwordx4 v[88:89], off
	v_lshl_add_u64 v[88:89], v[68:69], 0, v[64:65]
	v_lshl_add_u64 v[90:91], v[88:89], 0, s[18:19]
	s_mov_b32 m0, s4
	v_readfirstlane_b32 s4, v119
	global_load_lds_dwordx4 v[90:91], off
	v_lshl_add_u64 v[90:91], v[78:79], 0, v[64:65]
	v_lshl_add_u64 v[92:93], v[90:91], 0, s[18:19]
	s_mov_b32 m0, s4
	v_readfirstlane_b32 s4, v120
	global_load_lds_dwordx4 v[92:93], off
	v_lshl_add_u64 v[92:93], v[70:71], 0, v[64:65]
	v_lshl_add_u64 v[94:95], v[92:93], 0, s[18:19]
	s_mov_b32 m0, s4
	v_readfirstlane_b32 s4, v121
	global_load_lds_dwordx4 v[94:95], off
	v_lshl_add_u64 v[94:95], v[80:81], 0, v[64:65]
	v_lshl_add_u64 v[96:97], v[94:95], 0, s[18:19]
	s_mov_b32 m0, s4
	v_readfirstlane_b32 s4, v122
	global_load_lds_dwordx4 v[96:97], off
	v_lshl_add_u64 v[96:97], v[72:73], 0, v[64:65]
	v_lshl_add_u64 v[128:129], v[96:97], 0, s[18:19]
	s_mov_b32 m0, s4
	s_nop 0
	global_load_lds_dwordx4 v[128:129], off
	s_nop 0
	ds_read_b128 v[128:131], v123
	ds_read_b128 v[132:135], v123 offset:2048
	ds_read_b128 v[136:139], v123 offset:4096
	ds_read_b128 v[140:143], v123 offset:6144
	ds_read_b128 v[144:147], v124 offset:16384
	ds_read_b128 v[148:151], v124 offset:18432
	ds_read_b128 v[152:155], v124 offset:20480
	ds_read_b128 v[156:159], v124 offset:22528
	s_setprio 1
	s_waitcnt lgkmcnt(0)
	v_mfma_f32_16x16x32_bf16 v[60:63], v[144:147], v[128:131], v[60:63]
	v_mfma_f32_16x16x32_bf16 v[44:47], v[144:147], v[132:135], v[44:47]
	v_mfma_f32_16x16x32_bf16 v[28:31], v[144:147], v[136:139], v[28:31]
	v_mfma_f32_16x16x32_bf16 v[12:15], v[144:147], v[140:143], v[12:15]
	v_mfma_f32_16x16x32_bf16 v[56:59], v[148:151], v[128:131], v[56:59]
	v_mfma_f32_16x16x32_bf16 v[40:43], v[148:151], v[132:135], v[40:43]
	v_mfma_f32_16x16x32_bf16 v[24:27], v[148:151], v[136:139], v[24:27]
	v_mfma_f32_16x16x32_bf16 v[52:55], v[152:155], v[128:131], v[52:55]
	v_mfma_f32_16x16x32_bf16 v[36:39], v[152:155], v[132:135], v[36:39]
	v_mfma_f32_16x16x32_bf16 v[48:51], v[156:159], v[128:131], v[48:51]
	v_mfma_f32_16x16x32_bf16 v[144:147], v[148:151], v[140:143], v[8:11]
	v_mfma_f32_16x16x32_bf16 v[148:151], v[152:155], v[136:139], v[20:23]
	v_mfma_f32_16x16x32_bf16 v[152:155], v[152:155], v[140:143], v[4:7]
	v_mfma_f32_16x16x32_bf16 v[128:131], v[156:159], v[132:135], v[32:35]
	v_mfma_f32_16x16x32_bf16 v[132:135], v[156:159], v[136:139], v[16:19]
	v_mfma_f32_16x16x32_bf16 v[136:139], v[156:159], v[140:143], v[0:3]
	s_setprio 0
	ds_read_b128 v[140:143], v125
	ds_read_b128 v[156:159], v125 offset:2048
	ds_read_b128 v[160:163], v125 offset:4096
	ds_read_b128 v[164:167], v125 offset:6144
	ds_read_b128 v[16:19], v126 offset:16384
	ds_read_b128 v[32:35], v126 offset:18432
	ds_read_b128 v[168:171], v126 offset:20480
	ds_read_b128 v[172:175], v126 offset:22528
	s_setprio 1
	s_waitcnt lgkmcnt(3)
	v_mfma_f32_16x16x32_bf16 v[0:3], v[16:19], v[140:143], v[60:63]
	v_mfma_f32_16x16x32_bf16 v[4:7], v[16:19], v[156:159], v[44:47]
	v_mfma_f32_16x16x32_bf16 v[8:11], v[16:19], v[160:163], v[28:31]
	v_mfma_f32_16x16x32_bf16 v[12:15], v[16:19], v[164:167], v[12:15]
	s_waitcnt lgkmcnt(2)
	v_mfma_f32_16x16x32_bf16 v[16:19], v[32:35], v[140:143], v[56:59]
	v_mfma_f32_16x16x32_bf16 v[20:23], v[32:35], v[156:159], v[40:43]
	v_mfma_f32_16x16x32_bf16 v[24:27], v[32:35], v[160:163], v[24:27]
	v_mfma_f32_16x16x32_bf16 v[28:31], v[32:35], v[164:167], v[144:147]
	s_waitcnt lgkmcnt(1)
	v_mfma_f32_16x16x32_bf16 v[32:35], v[168:171], v[140:143], v[52:55]
	v_mfma_f32_16x16x32_bf16 v[36:39], v[168:171], v[156:159], v[36:39]
	v_mfma_f32_16x16x32_bf16 v[40:43], v[168:171], v[160:163], v[148:151]
	v_mfma_f32_16x16x32_bf16 v[44:47], v[168:171], v[164:167], v[152:155]
	s_waitcnt lgkmcnt(0)
	v_mfma_f32_16x16x32_bf16 v[48:51], v[172:175], v[140:143], v[48:51]
	v_mfma_f32_16x16x32_bf16 v[52:55], v[172:175], v[156:159], v[128:131]
	v_mfma_f32_16x16x32_bf16 v[56:59], v[172:175], v[160:163], v[132:135]
	v_mfma_f32_16x16x32_bf16 v[60:63], v[172:175], v[164:167], v[136:139]
	s_setprio 0
	s_waitcnt vmcnt(0)
	s_cmp_gt_u32 s9, 13
	s_cselect_b64 s[4:5], -1, 0
	s_and_b64 vcc, exec, s[4:5]
	s_barrier
	s_cbranch_vccnz .LBB0_258
	v_readfirstlane_b32 s10, v107
	v_lshl_add_u64 v[82:83], v[82:83], 0, s[20:21]
	s_mov_b32 m0, s10
	v_readfirstlane_b32 s10, v108
	global_load_lds_dwordx4 v[82:83], off
	v_lshl_add_u64 v[82:83], v[84:85], 0, s[20:21]
	s_mov_b32 m0, s10
	v_readfirstlane_b32 s10, v109
	global_load_lds_dwordx4 v[82:83], off
	v_lshl_add_u64 v[82:83], v[86:87], 0, s[20:21]
	s_mov_b32 m0, s10
	v_readfirstlane_b32 s10, v110
	global_load_lds_dwordx4 v[82:83], off
	v_lshl_add_u64 v[82:83], v[88:89], 0, s[20:21]
	s_mov_b32 m0, s10
	v_readfirstlane_b32 s10, v111
	global_load_lds_dwordx4 v[82:83], off
	v_lshl_add_u64 v[82:83], v[90:91], 0, s[20:21]
	s_mov_b32 m0, s10
	v_readfirstlane_b32 s10, v112
	global_load_lds_dwordx4 v[82:83], off
	v_lshl_add_u64 v[82:83], v[92:93], 0, s[20:21]
	s_mov_b32 m0, s10
	v_readfirstlane_b32 s10, v113
	global_load_lds_dwordx4 v[82:83], off
	v_lshl_add_u64 v[82:83], v[94:95], 0, s[20:21]
	s_mov_b32 m0, s10
	v_readfirstlane_b32 s10, v114
	global_load_lds_dwordx4 v[82:83], off
	v_lshl_add_u64 v[82:83], v[96:97], 0, s[20:21]
	s_mov_b32 m0, s10
	s_nop 0
	global_load_lds_dwordx4 v[82:83], off
	s_branch .LBB0_258

; template <bool DB, class AF>
; DEVI void gemm_mainloop(int tid, u16* sA, u16* sB, AF af, const u16* __restrict__ Bt, int ldb, int m0, int n0, int nk,
;                         f32x4 (&acc)[4][4]) {
;     ...
;     STAGE_(0, 0)
; #pragma unroll 1
;     for (int kt = 0; kt < nk; kt += 2) {
;       asm volatile("s_waitcnt vmcnt(0)" ::: "memory");
;       __syncthreads();
;       { const int kk = (kt + 1) * 64; STAGE_(1, kk) }
;       COMPUTE_SW_(0)
;       asm volatile("s_waitcnt vmcnt(0)" ::: "memory");
;       __syncthreads();
;       if (kt + 2 < nk) { const int kk = (kt + 2) * 64; STAGE_(0, kk) }
;       COMPUTE_SW_(1)
.LBB0_309:
	s_nop 0
	ds_read_b128 v[82:85], v106 offset:32768
	ds_read_b128 v[86:89], v106 offset:34816
	ds_read_b128 v[90:93], v106 offset:36864
	ds_read_b128 v[94:97], v106 offset:38912
	ds_read_b128 v[120:123], v116 offset:49152
	ds_read_b128 v[124:127], v116 offset:51200
	ds_read_b128 v[128:131], v116 offset:53248
	ds_read_b128 v[132:135], v116 offset:55296
	s_add_i32 s6, s6, 2
	s_setprio 1
	s_waitcnt lgkmcnt(0)
	v_mfma_f32_16x16x32_bf16 v[0:3], v[120:123], v[82:85], v[0:3]
	v_mfma_f32_16x16x32_bf16 v[4:7], v[120:123], v[86:89], v[4:7]
	v_mfma_f32_16x16x32_bf16 v[8:11], v[120:123], v[90:93], v[8:11]
	v_mfma_f32_16x16x32_bf16 v[12:15], v[120:123], v[94:97], v[12:15]
	v_mfma_f32_16x16x32_bf16 v[16:19], v[124:127], v[82:85], v[16:19]
	v_mfma_f32_16x16x32_bf16 v[20:23], v[124:127], v[86:89], v[20:23]
	v_mfma_f32_16x16x32_bf16 v[24:27], v[124:127], v[90:93], v[24:27]
	v_mfma_f32_16x16x32_bf16 v[32:35], v[128:131], v[82:85], v[32:35]
	v_mfma_f32_16x16x32_bf16 v[36:39], v[128:131], v[86:89], v[36:39]
	v_mfma_f32_16x16x32_bf16 v[48:51], v[132:135], v[82:85], v[48:51]
	v_mfma_f32_16x16x32_bf16 v[120:123], v[124:127], v[94:97], v[28:31]
	v_mfma_f32_16x16x32_bf16 v[124:127], v[128:131], v[90:93], v[40:43]
	v_mfma_f32_16x16x32_bf16 v[128:131], v[128:131], v[94:97], v[44:47]
	v_mfma_f32_16x16x32_bf16 v[82:85], v[132:135], v[86:89], v[52:55]
	v_mfma_f32_16x16x32_bf16 v[86:89], v[132:135], v[90:93], v[56:59]
	v_mfma_f32_16x16x32_bf16 v[90:93], v[132:135], v[94:97], v[60:63]
	s_setprio 0
	ds_read_b128 v[94:97], v117 offset:32768
	ds_read_b128 v[132:135], v117 offset:34816
	ds_read_b128 v[136:139], v117 offset:36864
	ds_read_b128 v[140:143], v117 offset:38912
	ds_read_b128 v[40:43], v118 offset:49152
	ds_read_b128 v[52:55], v118 offset:51200
	ds_read_b128 v[144:147], v118 offset:53248
	ds_read_b128 v[148:151], v118 offset:55296
	s_setprio 1
	s_waitcnt lgkmcnt(3)
	v_mfma_f32_16x16x32_bf16 v[60:63], v[40:43], v[94:97], v[0:3]
	v_mfma_f32_16x16x32_bf16 v[44:47], v[40:43], v[132:135], v[4:7]
	v_mfma_f32_16x16x32_bf16 v[28:31], v[40:43], v[136:139], v[8:11]
	v_mfma_f32_16x16x32_bf16 v[12:15], v[40:43], v[140:143], v[12:15]
	s_waitcnt lgkmcnt(2)
	v_mfma_f32_16x16x32_bf16 v[56:59], v[52:55], v[94:97], v[16:19]
	v_mfma_f32_16x16x32_bf16 v[40:43], v[52:55], v[132:135], v[20:23]
	v_mfma_f32_16x16x32_bf16 v[24:27], v[52:55], v[136:139], v[24:27]
	v_mfma_f32_16x16x32_bf16 v[8:11], v[52:55], v[140:143], v[120:123]
	s_waitcnt lgkmcnt(1)
	v_mfma_f32_16x16x32_bf16 v[52:55], v[144:147], v[94:97], v[32:35]
	v_mfma_f32_16x16x32_bf16 v[36:39], v[144:147], v[132:135], v[36:39]
	v_mfma_f32_16x16x32_bf16 v[20:23], v[144:147], v[136:139], v[124:127]
	v_mfma_f32_16x16x32_bf16 v[4:7], v[144:147], v[140:143], v[128:131]
	s_waitcnt lgkmcnt(0)
	v_mfma_f32_16x16x32_bf16 v[48:51], v[148:151], v[94:97], v[48:51]
	v_mfma_f32_16x16x32_bf16 v[32:35], v[148:151], v[132:135], v[82:85]
	v_mfma_f32_16x16x32_bf16 v[16:19], v[148:151], v[136:139], v[86:89]
	v_mfma_f32_16x16x32_bf16 v[0:3], v[148:151], v[140:143], v[90:93]
	s_setprio 0
	v_lshl_add_u64 v[66:67], v[66:67], 0, s[20:21]
	v_lshl_add_u64 v[68:69], v[68:69], 0, s[20:21]
	v_lshl_add_u64 v[70:71], v[70:71], 0, s[20:21]
	v_lshl_add_u64 v[72:73], v[72:73], 0, s[20:21]
	v_lshl_add_u64 v[74:75], v[74:75], 0, s[20:21]
	v_lshl_add_u64 v[76:77], v[76:77], 0, s[20:21]
	v_lshl_add_u64 v[78:79], v[78:79], 0, s[20:21]
	s_andn2_b64 vcc, exec, s[0:1]
	v_lshl_add_u64 v[80:81], v[80:81], 0, s[20:21]
	s_cbranch_vccz .LBB0_312
; template <bool DB, class AF>
; DEVI void gemm_mainloop(int tid, u16* sA, u16* sB, AF af, const u16* __restrict__ Bt, int ldb, int m0, int n0, int nk,
;                         f32x4 (&acc)[4][4]) {
;     ...
;     STAGE_(0, 0)
; #pragma unroll 1
;     for (int kt = 0; kt < nk; kt += 2) {
;       asm volatile("s_waitcnt vmcnt(0)" ::: "memory");
;       __syncthreads();
;       { const int kk = (kt + 1) * 64; STAGE_(1, kk) }
;       COMPUTE_SW_(0)
;       asm volatile("s_waitcnt vmcnt(0)" ::: "memory");
;       __syncthreads();
;       if (kt + 2 < nk) { const int kk = (kt + 2) * 64; STAGE_(0, kk) }
;       COMPUTE_SW_(1)
.LBB0_310:
	v_add_u32_e32 v86, 0x8000, v108
	v_lshl_add_u64 v[82:83], v[74:75], 0, v[64:65]
	v_readfirstlane_b32 s0, v86
	v_lshl_add_u64 v[84:85], v[82:83], 0, s[18:19]
	s_mov_b32 m0, s0
	v_add_u32_e32 v88, 0xc000, v108
	s_waitcnt vmcnt(0)
	s_waitcnt vmcnt(0) lgkmcnt(0)
	s_barrier
	global_load_lds_dwordx4 v[84:85], off
	v_lshl_add_u64 v[84:85], v[66:67], 0, v[64:65]
	v_readfirstlane_b32 s0, v88
	v_lshl_add_u64 v[86:87], v[84:85], 0, s[18:19]
	s_mov_b32 m0, s0
	v_add_u32_e32 v90, 0x9000, v108
	global_load_lds_dwordx4 v[86:87], off
	v_lshl_add_u64 v[86:87], v[76:77], 0, v[64:65]
	v_readfirstlane_b32 s0, v90
	v_lshl_add_u64 v[88:89], v[86:87], 0, s[18:19]
	s_mov_b32 m0, s0
	v_add_u32_e32 v92, 0xd000, v108
	global_load_lds_dwordx4 v[88:89], off
	v_lshl_add_u64 v[88:89], v[68:69], 0, v[64:65]
	v_readfirstlane_b32 s0, v92
	v_lshl_add_u64 v[90:91], v[88:89], 0, s[18:19]
	s_mov_b32 m0, s0
	v_add_u32_e32 v94, 0xa000, v108
	global_load_lds_dwordx4 v[90:91], off
	v_lshl_add_u64 v[90:91], v[78:79], 0, v[64:65]
	v_readfirstlane_b32 s0, v94
	v_lshl_add_u64 v[92:93], v[90:91], 0, s[18:19]
	s_mov_b32 m0, s0
	v_add_u32_e32 v96, 0xe000, v108
	global_load_lds_dwordx4 v[92:93], off
	v_lshl_add_u64 v[92:93], v[70:71], 0, v[64:65]
	v_readfirstlane_b32 s0, v96
	v_lshl_add_u64 v[94:95], v[92:93], 0, s[18:19]
	s_mov_b32 m0, s0
	v_add_u32_e32 v119, 0xb000, v108
	global_load_lds_dwordx4 v[94:95], off
	v_lshl_add_u64 v[94:95], v[80:81], 0, v[64:65]
	v_readfirstlane_b32 s0, v119
	v_lshl_add_u64 v[96:97], v[94:95], 0, s[18:19]
	s_mov_b32 m0, s0
	v_add_u32_e32 v119, 0xf000, v108
	global_load_lds_dwordx4 v[96:97], off
	v_lshl_add_u64 v[96:97], v[72:73], 0, v[64:65]
	v_readfirstlane_b32 s0, v119
	v_lshl_add_u64 v[120:121], v[96:97], 0, s[18:19]
	s_mov_b32 m0, s0
	s_nop 0
	global_load_lds_dwordx4 v[120:121], off
	s_nop 0
	ds_read_b128 v[120:123], v106
	ds_read_b128 v[124:127], v106 offset:2048
	ds_read_b128 v[128:131], v106 offset:4096
	ds_read_b128 v[132:135], v106 offset:6144
	ds_read_b128 v[136:139], v116 offset:16384
	ds_read_b128 v[140:143], v116 offset:18432
	ds_read_b128 v[144:147], v116 offset:20480
	ds_read_b128 v[148:151], v116 offset:22528
	s_setprio 1
	s_waitcnt lgkmcnt(0)
	v_mfma_f32_16x16x32_bf16 v[60:63], v[136:139], v[120:123], v[60:63]
	v_mfma_f32_16x16x32_bf16 v[44:47], v[136:139], v[124:127], v[44:47]
	v_mfma_f32_16x16x32_bf16 v[28:31], v[136:139], v[128:131], v[28:31]
	v_mfma_f32_16x16x32_bf16 v[12:15], v[136:139], v[132:135], v[12:15]
	v_mfma_f32_16x16x32_bf16 v[56:59], v[140:143], v[120:123], v[56:59]
	v_mfma_f32_16x16x32_bf16 v[40:43], v[140:143], v[124:127], v[40:43]
	v_mfma_f32_16x16x32_bf16 v[24:27], v[140:143], v[128:131], v[24:27]
	v_mfma_f32_16x16x32_bf16 v[52:55], v[144:147], v[120:123], v[52:55]
	v_mfma_f32_16x16x32_bf16 v[36:39], v[144:147], v[124:127], v[36:39]
	v_mfma_f32_16x16x32_bf16 v[48:51], v[148:151], v[120:123], v[48:51]
	v_mfma_f32_16x16x32_bf16 v[136:139], v[140:143], v[132:135], v[8:11]
	v_mfma_f32_16x16x32_bf16 v[140:143], v[144:147], v[128:131], v[20:23]
	v_mfma_f32_16x16x32_bf16 v[144:147], v[144:147], v[132:135], v[4:7]
	v_mfma_f32_16x16x32_bf16 v[120:123], v[148:151], v[124:127], v[32:35]
	v_mfma_f32_16x16x32_bf16 v[124:127], v[148:151], v[128:131], v[16:19]
	v_mfma_f32_16x16x32_bf16 v[128:131], v[148:151], v[132:135], v[0:3]
	s_setprio 0
	ds_read_b128 v[132:135], v117
	ds_read_b128 v[148:151], v117 offset:2048
	ds_read_b128 v[152:155], v117 offset:4096
	ds_read_b128 v[156:159], v117 offset:6144
	ds_read_b128 v[16:19], v118 offset:16384
	ds_read_b128 v[32:35], v118 offset:18432
	ds_read_b128 v[160:163], v118 offset:20480
	ds_read_b128 v[164:167], v118 offset:22528
	s_setprio 1
	s_waitcnt lgkmcnt(3)
	v_mfma_f32_16x16x32_bf16 v[0:3], v[16:19], v[132:135], v[60:63]
	v_mfma_f32_16x16x32_bf16 v[4:7], v[16:19], v[148:151], v[44:47]
	v_mfma_f32_16x16x32_bf16 v[8:11], v[16:19], v[152:155], v[28:31]
	v_mfma_f32_16x16x32_bf16 v[12:15], v[16:19], v[156:159], v[12:15]
	s_waitcnt lgkmcnt(2)
	v_mfma_f32_16x16x32_bf16 v[16:19], v[32:35], v[132:135], v[56:59]
	v_mfma_f32_16x16x32_bf16 v[20:23], v[32:35], v[148:151], v[40:43]
	v_mfma_f32_16x16x32_bf16 v[24:27], v[32:35], v[152:155], v[24:27]
	v_mfma_f32_16x16x32_bf16 v[28:31], v[32:35], v[156:159], v[136:139]
	s_waitcnt lgkmcnt(1)
	v_mfma_f32_16x16x32_bf16 v[32:35], v[160:163], v[132:135], v[52:55]
	v_mfma_f32_16x16x32_bf16 v[36:39], v[160:163], v[148:151], v[36:39]
	v_mfma_f32_16x16x32_bf16 v[40:43], v[160:163], v[152:155], v[140:143]
	v_mfma_f32_16x16x32_bf16 v[44:47], v[160:163], v[156:159], v[144:147]
	s_waitcnt lgkmcnt(0)
	v_mfma_f32_16x16x32_bf16 v[48:51], v[164:167], v[132:135], v[48:51]
	v_mfma_f32_16x16x32_bf16 v[52:55], v[164:167], v[148:151], v[120:123]
	v_mfma_f32_16x16x32_bf16 v[56:59], v[164:167], v[152:155], v[124:127]
	v_mfma_f32_16x16x32_bf16 v[60:63], v[164:167], v[156:159], v[128:131]
	s_setprio 0
	s_waitcnt vmcnt(0)
	s_cmp_gt_u32 s6, 13
	s_cselect_b64 s[0:1], -1, 0
	s_and_b64 vcc, exec, s[0:1]
	s_barrier
	s_cbranch_vccnz .LBB0_309
	v_readfirstlane_b32 s7, v108
	v_lshl_add_u64 v[82:83], v[82:83], 0, s[20:21]
	s_mov_b32 m0, s7
	v_readfirstlane_b32 s7, v109
	global_load_lds_dwordx4 v[82:83], off
	v_lshl_add_u64 v[82:83], v[84:85], 0, s[20:21]
	s_mov_b32 m0, s7
	v_readfirstlane_b32 s7, v110
	global_load_lds_dwordx4 v[82:83], off
	v_lshl_add_u64 v[82:83], v[86:87], 0, s[20:21]
	s_mov_b32 m0, s7
	v_readfirstlane_b32 s7, v111
	global_load_lds_dwordx4 v[82:83], off
	v_lshl_add_u64 v[82:83], v[88:89], 0, s[20:21]
	s_mov_b32 m0, s7
	v_readfirstlane_b32 s7, v112
	global_load_lds_dwordx4 v[82:83], off
	v_lshl_add_u64 v[82:83], v[90:91], 0, s[20:21]
	s_mov_b32 m0, s7
	v_readfirstlane_b32 s7, v113
	global_load_lds_dwordx4 v[82:83], off
	v_lshl_add_u64 v[82:83], v[92:93], 0, s[20:21]
	s_mov_b32 m0, s7
	v_readfirstlane_b32 s7, v114
	global_load_lds_dwordx4 v[82:83], off
	v_lshl_add_u64 v[82:83], v[94:95], 0, s[20:21]
	s_mov_b32 m0, s7
	v_readfirstlane_b32 s7, v115
	global_load_lds_dwordx4 v[82:83], off
	v_lshl_add_u64 v[82:83], v[96:97], 0, s[20:21]
	s_mov_b32 m0, s7
	s_nop 0
	global_load_lds_dwordx4 v[82:83], off
	s_branch .LBB0_309

; template <bool DB, class AF>
; DEVI void gemm_mainloop(int tid, u16* sA, u16* sB, AF af, const u16* __restrict__ Bt, int ldb, int m0, int n0, int nk,
;                         f32x4 (&acc)[4][4]) {
;     ...
;     STAGE_(0, 0)
; #pragma unroll 1
;     for (int kt = 0; kt < nk; kt += 2) {
;       asm volatile("s_waitcnt vmcnt(0)" ::: "memory");
;       __syncthreads();
;       { const int kk = (kt + 1) * 64; STAGE_(1, kk) }
;       COMPUTE_SW_(0)
;       asm volatile("s_waitcnt vmcnt(0)" ::: "memory");
;       __syncthreads();
;       if (kt + 2 < nk) { const int kk = (kt + 2) * 64; STAGE_(0, kk) }
;       COMPUTE_SW_(1)
.LBB0_626:
	s_nop 0
	ds_read_b128 v[82:85], v106 offset:32768
	ds_read_b128 v[86:89], v106 offset:34816
	ds_read_b128 v[90:93], v106 offset:36864
	ds_read_b128 v[94:97], v106 offset:38912
	ds_read_b128 v[110:113], v107 offset:49152
	ds_read_b128 v[114:117], v107 offset:51200
	ds_read_b128 v[118:121], v107 offset:53248
	ds_read_b128 v[122:125], v107 offset:55296
	s_add_i32 s33, s33, 2
	s_setprio 1
	s_waitcnt lgkmcnt(0)
	v_mfma_f32_16x16x32_bf16 v[0:3], v[110:113], v[82:85], v[0:3]
	v_mfma_f32_16x16x32_bf16 v[4:7], v[110:113], v[86:89], v[4:7]
	v_mfma_f32_16x16x32_bf16 v[8:11], v[110:113], v[90:93], v[8:11]
	v_mfma_f32_16x16x32_bf16 v[12:15], v[110:113], v[94:97], v[12:15]
	v_mfma_f32_16x16x32_bf16 v[16:19], v[114:117], v[82:85], v[16:19]
	v_mfma_f32_16x16x32_bf16 v[20:23], v[114:117], v[86:89], v[20:23]
	v_mfma_f32_16x16x32_bf16 v[24:27], v[114:117], v[90:93], v[24:27]
	v_mfma_f32_16x16x32_bf16 v[32:35], v[118:121], v[82:85], v[32:35]
	v_mfma_f32_16x16x32_bf16 v[36:39], v[118:121], v[86:89], v[36:39]
	v_mfma_f32_16x16x32_bf16 v[48:51], v[122:125], v[82:85], v[48:51]
	v_mfma_f32_16x16x32_bf16 v[110:113], v[114:117], v[94:97], v[28:31]
	v_mfma_f32_16x16x32_bf16 v[114:117], v[118:121], v[90:93], v[40:43]
	v_mfma_f32_16x16x32_bf16 v[118:121], v[118:121], v[94:97], v[44:47]
	v_mfma_f32_16x16x32_bf16 v[82:85], v[122:125], v[86:89], v[52:55]
	v_mfma_f32_16x16x32_bf16 v[86:89], v[122:125], v[90:93], v[56:59]
	v_mfma_f32_16x16x32_bf16 v[90:93], v[122:125], v[94:97], v[60:63]
	s_setprio 0
	ds_read_b128 v[94:97], v108 offset:32768
	ds_read_b128 v[122:125], v108 offset:34816
	ds_read_b128 v[126:129], v108 offset:36864
	ds_read_b128 v[130:133], v108 offset:38912
	ds_read_b128 v[40:43], v109 offset:49152
	ds_read_b128 v[52:55], v109 offset:51200
	ds_read_b128 v[134:137], v109 offset:53248
	ds_read_b128 v[138:141], v109 offset:55296
	s_setprio 1
	s_waitcnt lgkmcnt(3)
	v_mfma_f32_16x16x32_bf16 v[60:63], v[40:43], v[94:97], v[0:3]
	v_mfma_f32_16x16x32_bf16 v[44:47], v[40:43], v[122:125], v[4:7]
	v_mfma_f32_16x16x32_bf16 v[28:31], v[40:43], v[126:129], v[8:11]
	v_mfma_f32_16x16x32_bf16 v[12:15], v[40:43], v[130:133], v[12:15]
	s_waitcnt lgkmcnt(2)
	v_mfma_f32_16x16x32_bf16 v[56:59], v[52:55], v[94:97], v[16:19]
	v_mfma_f32_16x16x32_bf16 v[40:43], v[52:55], v[122:125], v[20:23]
	v_mfma_f32_16x16x32_bf16 v[24:27], v[52:55], v[126:129], v[24:27]
	v_mfma_f32_16x16x32_bf16 v[8:11], v[52:55], v[130:133], v[110:113]
	s_waitcnt lgkmcnt(1)
	v_mfma_f32_16x16x32_bf16 v[52:55], v[134:137], v[94:97], v[32:35]
	v_mfma_f32_16x16x32_bf16 v[36:39], v[134:137], v[122:125], v[36:39]
	v_mfma_f32_16x16x32_bf16 v[20:23], v[134:137], v[126:129], v[114:117]
	v_mfma_f32_16x16x32_bf16 v[4:7], v[134:137], v[130:133], v[118:121]
	s_waitcnt lgkmcnt(0)
	v_mfma_f32_16x16x32_bf16 v[48:51], v[138:141], v[94:97], v[48:51]
	v_mfma_f32_16x16x32_bf16 v[32:35], v[138:141], v[122:125], v[82:85]
	v_mfma_f32_16x16x32_bf16 v[16:19], v[138:141], v[126:129], v[86:89]
	v_mfma_f32_16x16x32_bf16 v[0:3], v[138:141], v[130:133], v[90:93]
	s_setprio 0
	v_lshl_add_u64 v[66:67], v[66:67], 0, s[18:19]
	v_lshl_add_u64 v[68:69], v[68:69], 0, s[18:19]
	v_lshl_add_u64 v[70:71], v[70:71], 0, s[18:19]
	v_lshl_add_u64 v[72:73], v[72:73], 0, s[18:19]
	v_lshl_add_u64 v[74:75], v[74:75], 0, s[20:21]
	v_lshl_add_u64 v[76:77], v[76:77], 0, s[20:21]
	v_lshl_add_u64 v[78:79], v[78:79], 0, s[20:21]
	s_andn2_b64 vcc, exec, s[0:1]
	v_lshl_add_u64 v[80:81], v[80:81], 0, s[20:21]
	s_cbranch_vccz .LBB0_629
; template <bool DB, class AF>
; DEVI void gemm_mainloop(int tid, u16* sA, u16* sB, AF af, const u16* __restrict__ Bt, int ldb, int m0, int n0, int nk,
;                         f32x4 (&acc)[4][4]) {
;     ...
;     STAGE_(0, 0)
; #pragma unroll 1
;     for (int kt = 0; kt < nk; kt += 2) {
;       asm volatile("s_waitcnt vmcnt(0)" ::: "memory");
;       __syncthreads();
;       { const int kk = (kt + 1) * 64; STAGE_(1, kk) }
;       COMPUTE_SW_(0)
;       asm volatile("s_waitcnt vmcnt(0)" ::: "memory");
;       __syncthreads();
;       if (kt + 2 < nk) { const int kk = (kt + 2) * 64; STAGE_(0, kk) }
;       COMPUTE_SW_(1)
.LBB0_627:
	v_add_u32_e32 v86, 0x8000, v98
	v_lshl_add_u64 v[82:83], v[72:73], 0, v[64:65]
	v_readfirstlane_b32 s0, v86
	v_lshl_add_u64 v[84:85], v[82:83], 0, s[12:13]
	s_mov_b32 m0, s0
	v_add_u32_e32 v88, 0xc000, v98
	s_waitcnt vmcnt(0)
	s_waitcnt vmcnt(0) lgkmcnt(0)
	s_barrier
	global_load_lds_dwordx4 v[84:85], off
	v_lshl_add_u64 v[84:85], v[74:75], 0, v[64:65]
	v_readfirstlane_b32 s0, v88
	v_lshl_add_u64 v[86:87], v[84:85], 0, s[14:15]
	s_mov_b32 m0, s0
	v_add_u32_e32 v90, 0x9000, v98
	global_load_lds_dwordx4 v[86:87], off
	v_lshl_add_u64 v[86:87], v[70:71], 0, v[64:65]
	v_readfirstlane_b32 s0, v90
	v_lshl_add_u64 v[88:89], v[86:87], 0, s[12:13]
	s_mov_b32 m0, s0
	v_add_u32_e32 v92, 0xd000, v98
	global_load_lds_dwordx4 v[88:89], off
	v_lshl_add_u64 v[88:89], v[76:77], 0, v[64:65]
	v_readfirstlane_b32 s0, v92
	v_lshl_add_u64 v[90:91], v[88:89], 0, s[14:15]
	s_mov_b32 m0, s0
	v_add_u32_e32 v94, 0xa000, v98
	global_load_lds_dwordx4 v[90:91], off
	v_lshl_add_u64 v[90:91], v[68:69], 0, v[64:65]
	v_readfirstlane_b32 s0, v94
	v_lshl_add_u64 v[92:93], v[90:91], 0, s[12:13]
	s_mov_b32 m0, s0
	v_add_u32_e32 v96, 0xe000, v98
	global_load_lds_dwordx4 v[92:93], off
	v_lshl_add_u64 v[92:93], v[78:79], 0, v[64:65]
	v_readfirstlane_b32 s0, v96
	v_lshl_add_u64 v[94:95], v[92:93], 0, s[14:15]
	s_mov_b32 m0, s0
	v_add_u32_e32 v110, 0xb000, v98
	global_load_lds_dwordx4 v[94:95], off
	v_lshl_add_u64 v[94:95], v[66:67], 0, v[64:65]
	v_readfirstlane_b32 s0, v110
	v_lshl_add_u64 v[96:97], v[94:95], 0, s[12:13]
	s_mov_b32 m0, s0
	v_add_u32_e32 v112, 0xf000, v98
	global_load_lds_dwordx4 v[96:97], off
	v_lshl_add_u64 v[96:97], v[80:81], 0, v[64:65]
	v_readfirstlane_b32 s0, v112
	v_lshl_add_u64 v[110:111], v[96:97], 0, s[14:15]
	s_mov_b32 m0, s0
	s_nop 0
	global_load_lds_dwordx4 v[110:111], off
	s_nop 0
	ds_read_b128 v[110:113], v106
	ds_read_b128 v[114:117], v106 offset:2048
	ds_read_b128 v[118:121], v106 offset:4096
	ds_read_b128 v[122:125], v106 offset:6144
	ds_read_b128 v[126:129], v107 offset:16384
	ds_read_b128 v[130:133], v107 offset:18432
	ds_read_b128 v[134:137], v107 offset:20480
	ds_read_b128 v[138:141], v107 offset:22528
	s_setprio 1
	s_waitcnt lgkmcnt(0)
	v_mfma_f32_16x16x32_bf16 v[60:63], v[126:129], v[110:113], v[60:63]
	v_mfma_f32_16x16x32_bf16 v[44:47], v[126:129], v[114:117], v[44:47]
	v_mfma_f32_16x16x32_bf16 v[28:31], v[126:129], v[118:121], v[28:31]
	v_mfma_f32_16x16x32_bf16 v[12:15], v[126:129], v[122:125], v[12:15]
	v_mfma_f32_16x16x32_bf16 v[56:59], v[130:133], v[110:113], v[56:59]
	v_mfma_f32_16x16x32_bf16 v[40:43], v[130:133], v[114:117], v[40:43]
	v_mfma_f32_16x16x32_bf16 v[24:27], v[130:133], v[118:121], v[24:27]
	v_mfma_f32_16x16x32_bf16 v[52:55], v[134:137], v[110:113], v[52:55]
	v_mfma_f32_16x16x32_bf16 v[36:39], v[134:137], v[114:117], v[36:39]
	v_mfma_f32_16x16x32_bf16 v[48:51], v[138:141], v[110:113], v[48:51]
	v_mfma_f32_16x16x32_bf16 v[126:129], v[130:133], v[122:125], v[8:11]
	v_mfma_f32_16x16x32_bf16 v[130:133], v[134:137], v[118:121], v[20:23]
	v_mfma_f32_16x16x32_bf16 v[134:137], v[134:137], v[122:125], v[4:7]
	v_mfma_f32_16x16x32_bf16 v[110:113], v[138:141], v[114:117], v[32:35]
	v_mfma_f32_16x16x32_bf16 v[114:117], v[138:141], v[118:121], v[16:19]
	v_mfma_f32_16x16x32_bf16 v[118:121], v[138:141], v[122:125], v[0:3]
	s_setprio 0
	ds_read_b128 v[122:125], v108
	ds_read_b128 v[138:141], v108 offset:2048
	ds_read_b128 v[142:145], v108 offset:4096
	ds_read_b128 v[146:149], v108 offset:6144
	ds_read_b128 v[16:19], v109 offset:16384
	ds_read_b128 v[32:35], v109 offset:18432
	ds_read_b128 v[150:153], v109 offset:20480
	ds_read_b128 v[154:157], v109 offset:22528
	s_setprio 1
	s_waitcnt lgkmcnt(3)
	v_mfma_f32_16x16x32_bf16 v[0:3], v[16:19], v[122:125], v[60:63]
	v_mfma_f32_16x16x32_bf16 v[4:7], v[16:19], v[138:141], v[44:47]
	v_mfma_f32_16x16x32_bf16 v[8:11], v[16:19], v[142:145], v[28:31]
	v_mfma_f32_16x16x32_bf16 v[12:15], v[16:19], v[146:149], v[12:15]
	s_waitcnt lgkmcnt(2)
	v_mfma_f32_16x16x32_bf16 v[16:19], v[32:35], v[122:125], v[56:59]
	v_mfma_f32_16x16x32_bf16 v[20:23], v[32:35], v[138:141], v[40:43]
	v_mfma_f32_16x16x32_bf16 v[24:27], v[32:35], v[142:145], v[24:27]
	v_mfma_f32_16x16x32_bf16 v[28:31], v[32:35], v[146:149], v[126:129]
	s_waitcnt lgkmcnt(1)
	v_mfma_f32_16x16x32_bf16 v[32:35], v[150:153], v[122:125], v[52:55]
	v_mfma_f32_16x16x32_bf16 v[36:39], v[150:153], v[138:141], v[36:39]
	v_mfma_f32_16x16x32_bf16 v[40:43], v[150:153], v[142:145], v[130:133]
	v_mfma_f32_16x16x32_bf16 v[44:47], v[150:153], v[146:149], v[134:137]
	s_waitcnt lgkmcnt(0)
	v_mfma_f32_16x16x32_bf16 v[48:51], v[154:157], v[122:125], v[48:51]
	v_mfma_f32_16x16x32_bf16 v[52:55], v[154:157], v[138:141], v[110:113]
	v_mfma_f32_16x16x32_bf16 v[56:59], v[154:157], v[142:145], v[114:117]
	v_mfma_f32_16x16x32_bf16 v[60:63], v[154:157], v[146:149], v[118:121]
	s_setprio 0
	s_waitcnt vmcnt(0)
	s_cmp_gt_u32 s33, 29
	s_cselect_b64 s[0:1], -1, 0
	s_and_b64 vcc, exec, s[0:1]
	s_barrier
	s_cbranch_vccnz .LBB0_626
	v_readfirstlane_b32 s22, v98
	v_lshl_add_u64 v[82:83], v[82:83], 0, s[18:19]
	s_mov_b32 m0, s22
	v_readfirstlane_b32 s22, v99
	global_load_lds_dwordx4 v[82:83], off
	v_lshl_add_u64 v[82:83], v[84:85], 0, s[20:21]
	s_mov_b32 m0, s22
	v_readfirstlane_b32 s22, v100
	global_load_lds_dwordx4 v[82:83], off
	v_lshl_add_u64 v[82:83], v[86:87], 0, s[18:19]
	s_mov_b32 m0, s22
	v_readfirstlane_b32 s22, v101
	global_load_lds_dwordx4 v[82:83], off
	v_lshl_add_u64 v[82:83], v[88:89], 0, s[20:21]
	s_mov_b32 m0, s22
	v_readfirstlane_b32 s22, v102
	global_load_lds_dwordx4 v[82:83], off
	v_lshl_add_u64 v[82:83], v[90:91], 0, s[18:19]
	s_mov_b32 m0, s22
	v_readfirstlane_b32 s22, v103
	global_load_lds_dwordx4 v[82:83], off
	v_lshl_add_u64 v[82:83], v[92:93], 0, s[20:21]
	s_mov_b32 m0, s22
	v_readfirstlane_b32 s22, v104
	global_load_lds_dwordx4 v[82:83], off
	v_lshl_add_u64 v[82:83], v[94:95], 0, s[18:19]
	s_mov_b32 m0, s22
	v_readfirstlane_b32 s22, v105
	global_load_lds_dwordx4 v[82:83], off
	v_lshl_add_u64 v[82:83], v[96:97], 0, s[20:21]
	s_mov_b32 m0, s22
	s_nop 0
	global_load_lds_dwordx4 v[82:83], off
	s_branch .LBB0_626

; template <bool DB, class AF>
; DEVI void gemm_mainloop(int tid, u16* sA, u16* sB, AF af, const u16* __restrict__ Bt, int ldb, int m0, int n0, int nk,
;                         f32x4 (&acc)[4][4]) {
;     ...
;     STAGE_(0, 0)
; #pragma unroll 1
;     for (int kt = 0; kt < nk; kt += 2) {
;       asm volatile("s_waitcnt vmcnt(0)" ::: "memory");
;       __syncthreads();
;       { const int kk = (kt + 1) * 64; STAGE_(1, kk) }
;       COMPUTE_SW_(0)
;       asm volatile("s_waitcnt vmcnt(0)" ::: "memory");
;       __syncthreads();
;       if (kt + 2 < nk) { const int kk = (kt + 2) * 64; STAGE_(0, kk) }
;       COMPUTE_SW_(1)
.LBB0_893:
	s_nop 0
	ds_read_b128 v[86:89], v122 offset:32768
	ds_read_b128 v[90:93], v122 offset:34816
	ds_read_b128 v[94:97], v122 offset:36864
	ds_read_b128 v[98:101], v122 offset:38912
	ds_read_b128 v[126:129], v123 offset:49152
	ds_read_b128 v[130:133], v123 offset:51200
	ds_read_b128 v[134:137], v123 offset:53248
	ds_read_b128 v[138:141], v123 offset:55296
	s_add_i32 s19, s19, 2
	s_setprio 1
	s_waitcnt lgkmcnt(0)
	v_mfma_f32_16x16x32_bf16 v[0:3], v[126:129], v[86:89], v[0:3]
	v_mfma_f32_16x16x32_bf16 v[4:7], v[126:129], v[90:93], v[4:7]
	v_mfma_f32_16x16x32_bf16 v[8:11], v[126:129], v[94:97], v[8:11]
	v_mfma_f32_16x16x32_bf16 v[12:15], v[126:129], v[98:101], v[12:15]
	v_mfma_f32_16x16x32_bf16 v[16:19], v[130:133], v[86:89], v[16:19]
	v_mfma_f32_16x16x32_bf16 v[20:23], v[130:133], v[90:93], v[20:23]
	v_mfma_f32_16x16x32_bf16 v[24:27], v[130:133], v[94:97], v[24:27]
	v_mfma_f32_16x16x32_bf16 v[32:35], v[134:137], v[86:89], v[32:35]
	v_mfma_f32_16x16x32_bf16 v[36:39], v[134:137], v[90:93], v[36:39]
	v_mfma_f32_16x16x32_bf16 v[48:51], v[138:141], v[86:89], v[48:51]
	v_mfma_f32_16x16x32_bf16 v[126:129], v[130:133], v[98:101], v[28:31]
	v_mfma_f32_16x16x32_bf16 v[130:133], v[134:137], v[94:97], v[40:43]
	v_mfma_f32_16x16x32_bf16 v[134:137], v[134:137], v[98:101], v[44:47]
	v_mfma_f32_16x16x32_bf16 v[86:89], v[138:141], v[90:93], v[52:55]
	v_mfma_f32_16x16x32_bf16 v[90:93], v[138:141], v[94:97], v[56:59]
	v_mfma_f32_16x16x32_bf16 v[94:97], v[138:141], v[98:101], v[60:63]
	s_setprio 0
	ds_read_b128 v[98:101], v124 offset:32768
	ds_read_b128 v[138:141], v124 offset:34816
	ds_read_b128 v[142:145], v124 offset:36864
	ds_read_b128 v[146:149], v124 offset:38912
	ds_read_b128 v[40:43], v125 offset:49152
	ds_read_b128 v[52:55], v125 offset:51200
	ds_read_b128 v[150:153], v125 offset:53248
	ds_read_b128 v[154:157], v125 offset:55296
	s_setprio 1
	s_waitcnt lgkmcnt(3)
	v_mfma_f32_16x16x32_bf16 v[60:63], v[40:43], v[98:101], v[0:3]
	v_mfma_f32_16x16x32_bf16 v[44:47], v[40:43], v[138:141], v[4:7]
	v_mfma_f32_16x16x32_bf16 v[28:31], v[40:43], v[142:145], v[8:11]
	v_mfma_f32_16x16x32_bf16 v[12:15], v[40:43], v[146:149], v[12:15]
	s_waitcnt lgkmcnt(2)
	v_mfma_f32_16x16x32_bf16 v[56:59], v[52:55], v[98:101], v[16:19]
	v_mfma_f32_16x16x32_bf16 v[40:43], v[52:55], v[138:141], v[20:23]
	v_mfma_f32_16x16x32_bf16 v[24:27], v[52:55], v[142:145], v[24:27]
	v_mfma_f32_16x16x32_bf16 v[8:11], v[52:55], v[146:149], v[126:129]
	s_waitcnt lgkmcnt(1)
	v_mfma_f32_16x16x32_bf16 v[52:55], v[150:153], v[98:101], v[32:35]
	v_mfma_f32_16x16x32_bf16 v[36:39], v[150:153], v[138:141], v[36:39]
	v_mfma_f32_16x16x32_bf16 v[20:23], v[150:153], v[142:145], v[130:133]
	v_mfma_f32_16x16x32_bf16 v[4:7], v[150:153], v[146:149], v[134:137]
	s_waitcnt lgkmcnt(0)
	v_mfma_f32_16x16x32_bf16 v[48:51], v[154:157], v[98:101], v[48:51]
	v_mfma_f32_16x16x32_bf16 v[32:35], v[154:157], v[138:141], v[86:89]
	v_mfma_f32_16x16x32_bf16 v[16:19], v[154:157], v[142:145], v[90:93]
	v_mfma_f32_16x16x32_bf16 v[0:3], v[154:157], v[146:149], v[94:97]
	s_setprio 0
	v_lshl_add_u64 v[70:71], v[70:71], 0, s[8:9]
	v_lshl_add_u64 v[72:73], v[72:73], 0, s[8:9]
	v_lshl_add_u64 v[74:75], v[74:75], 0, s[8:9]
	v_lshl_add_u64 v[76:77], v[76:77], 0, s[8:9]
	v_lshl_add_u64 v[78:79], v[78:79], 0, s[8:9]
	v_lshl_add_u64 v[80:81], v[80:81], 0, s[8:9]
	v_lshl_add_u64 v[82:83], v[82:83], 0, s[8:9]
	s_andn2_b64 vcc, exec, s[4:5]
	v_lshl_add_u64 v[84:85], v[84:85], 0, s[8:9]
	s_cbranch_vccz .LBB0_896
; template <bool DB, class AF>
; DEVI void gemm_mainloop(int tid, u16* sA, u16* sB, AF af, const u16* __restrict__ Bt, int ldb, int m0, int n0, int nk,
;                         f32x4 (&acc)[4][4]) {
;     ...
;     STAGE_(0, 0)
; #pragma unroll 1
;     for (int kt = 0; kt < nk; kt += 2) {
;       asm volatile("s_waitcnt vmcnt(0)" ::: "memory");
;       __syncthreads();
;       { const int kk = (kt + 1) * 64; STAGE_(1, kk) }
;       COMPUTE_SW_(0)
;       asm volatile("s_waitcnt vmcnt(0)" ::: "memory");
;       __syncthreads();
;       if (kt + 2 < nk) { const int kk = (kt + 2) * 64; STAGE_(0, kk) }
;       COMPUTE_SW_(1)
.LBB0_894:
	v_lshl_add_u64 v[86:87], v[78:79], 0, v[64:65]
	v_readfirstlane_b32 s4, v114
	v_lshl_add_u64 v[88:89], v[86:87], 0, s[6:7]
	s_mov_b32 m0, s4
	s_waitcnt vmcnt(0)
	s_waitcnt vmcnt(0) lgkmcnt(0)
	s_barrier
	global_load_lds_dwordx4 v[88:89], off
	v_lshl_add_u64 v[88:89], v[70:71], 0, v[64:65]
	v_readfirstlane_b32 s4, v115
	v_lshl_add_u64 v[90:91], v[88:89], 0, s[6:7]
	s_mov_b32 m0, s4
	v_readfirstlane_b32 s4, v116
	global_load_lds_dwordx4 v[90:91], off
	v_lshl_add_u64 v[90:91], v[80:81], 0, v[64:65]
	v_lshl_add_u64 v[92:93], v[90:91], 0, s[6:7]
	s_mov_b32 m0, s4
	v_readfirstlane_b32 s4, v117
	global_load_lds_dwordx4 v[92:93], off
	v_lshl_add_u64 v[92:93], v[72:73], 0, v[64:65]
	v_lshl_add_u64 v[94:95], v[92:93], 0, s[6:7]
	s_mov_b32 m0, s4
	v_readfirstlane_b32 s4, v118
	global_load_lds_dwordx4 v[94:95], off
	v_lshl_add_u64 v[94:95], v[82:83], 0, v[64:65]
	v_lshl_add_u64 v[96:97], v[94:95], 0, s[6:7]
	s_mov_b32 m0, s4
	v_readfirstlane_b32 s4, v119
	global_load_lds_dwordx4 v[96:97], off
	v_lshl_add_u64 v[96:97], v[74:75], 0, v[64:65]
	v_lshl_add_u64 v[98:99], v[96:97], 0, s[6:7]
	s_mov_b32 m0, s4
	v_readfirstlane_b32 s4, v120
	global_load_lds_dwordx4 v[98:99], off
	v_lshl_add_u64 v[98:99], v[84:85], 0, v[64:65]
	v_lshl_add_u64 v[100:101], v[98:99], 0, s[6:7]
	s_mov_b32 m0, s4
	v_readfirstlane_b32 s4, v121
	global_load_lds_dwordx4 v[100:101], off
	v_lshl_add_u64 v[100:101], v[76:77], 0, v[64:65]
	v_lshl_add_u64 v[126:127], v[100:101], 0, s[6:7]
	s_mov_b32 m0, s4
	s_nop 0
	global_load_lds_dwordx4 v[126:127], off
	s_nop 0
	ds_read_b128 v[126:129], v122
	ds_read_b128 v[130:133], v122 offset:2048
	ds_read_b128 v[134:137], v122 offset:4096
	ds_read_b128 v[138:141], v122 offset:6144
	ds_read_b128 v[142:145], v123 offset:16384
	ds_read_b128 v[146:149], v123 offset:18432
	ds_read_b128 v[150:153], v123 offset:20480
	ds_read_b128 v[154:157], v123 offset:22528
	s_setprio 1
	s_waitcnt lgkmcnt(0)
	v_mfma_f32_16x16x32_bf16 v[60:63], v[142:145], v[126:129], v[60:63]
	v_mfma_f32_16x16x32_bf16 v[44:47], v[142:145], v[130:133], v[44:47]
	v_mfma_f32_16x16x32_bf16 v[28:31], v[142:145], v[134:137], v[28:31]
	v_mfma_f32_16x16x32_bf16 v[12:15], v[142:145], v[138:141], v[12:15]
	v_mfma_f32_16x16x32_bf16 v[56:59], v[146:149], v[126:129], v[56:59]
	v_mfma_f32_16x16x32_bf16 v[40:43], v[146:149], v[130:133], v[40:43]
	v_mfma_f32_16x16x32_bf16 v[24:27], v[146:149], v[134:137], v[24:27]
	v_mfma_f32_16x16x32_bf16 v[52:55], v[150:153], v[126:129], v[52:55]
	v_mfma_f32_16x16x32_bf16 v[36:39], v[150:153], v[130:133], v[36:39]
	v_mfma_f32_16x16x32_bf16 v[48:51], v[154:157], v[126:129], v[48:51]
	v_mfma_f32_16x16x32_bf16 v[142:145], v[146:149], v[138:141], v[8:11]
	v_mfma_f32_16x16x32_bf16 v[146:149], v[150:153], v[134:137], v[20:23]
	v_mfma_f32_16x16x32_bf16 v[150:153], v[150:153], v[138:141], v[4:7]
	v_mfma_f32_16x16x32_bf16 v[126:129], v[154:157], v[130:133], v[32:35]
	v_mfma_f32_16x16x32_bf16 v[130:133], v[154:157], v[134:137], v[16:19]
	v_mfma_f32_16x16x32_bf16 v[134:137], v[154:157], v[138:141], v[0:3]
	s_setprio 0
	ds_read_b128 v[138:141], v124
	ds_read_b128 v[154:157], v124 offset:2048
	ds_read_b128 v[158:161], v124 offset:4096
	ds_read_b128 v[162:165], v124 offset:6144
	ds_read_b128 v[16:19], v125 offset:16384
	ds_read_b128 v[32:35], v125 offset:18432
	ds_read_b128 v[166:169], v125 offset:20480
	ds_read_b128 v[170:173], v125 offset:22528
	s_setprio 1
	s_waitcnt lgkmcnt(3)
	v_mfma_f32_16x16x32_bf16 v[0:3], v[16:19], v[138:141], v[60:63]
	v_mfma_f32_16x16x32_bf16 v[4:7], v[16:19], v[154:157], v[44:47]
	v_mfma_f32_16x16x32_bf16 v[8:11], v[16:19], v[158:161], v[28:31]
	v_mfma_f32_16x16x32_bf16 v[12:15], v[16:19], v[162:165], v[12:15]
	s_waitcnt lgkmcnt(2)
	v_mfma_f32_16x16x32_bf16 v[16:19], v[32:35], v[138:141], v[56:59]
	v_mfma_f32_16x16x32_bf16 v[20:23], v[32:35], v[154:157], v[40:43]
	v_mfma_f32_16x16x32_bf16 v[24:27], v[32:35], v[158:161], v[24:27]
	v_mfma_f32_16x16x32_bf16 v[28:31], v[32:35], v[162:165], v[142:145]
	s_waitcnt lgkmcnt(1)
	v_mfma_f32_16x16x32_bf16 v[32:35], v[166:169], v[138:141], v[52:55]
	v_mfma_f32_16x16x32_bf16 v[36:39], v[166:169], v[154:157], v[36:39]
	v_mfma_f32_16x16x32_bf16 v[40:43], v[166:169], v[158:161], v[146:149]
	v_mfma_f32_16x16x32_bf16 v[44:47], v[166:169], v[162:165], v[150:153]
	s_waitcnt lgkmcnt(0)
	v_mfma_f32_16x16x32_bf16 v[48:51], v[170:173], v[138:141], v[48:51]
	v_mfma_f32_16x16x32_bf16 v[52:55], v[170:173], v[154:157], v[126:129]
	v_mfma_f32_16x16x32_bf16 v[56:59], v[170:173], v[158:161], v[130:133]
	v_mfma_f32_16x16x32_bf16 v[60:63], v[170:173], v[162:165], v[134:137]
	s_setprio 0
	s_waitcnt vmcnt(0)
	s_cmp_gt_u32 s19, 13
	s_cselect_b64 s[4:5], -1, 0
	s_and_b64 vcc, exec, s[4:5]
	s_barrier
	s_cbranch_vccnz .LBB0_893
	v_readfirstlane_b32 s20, v106
	v_lshl_add_u64 v[86:87], v[86:87], 0, s[8:9]
	s_mov_b32 m0, s20
	v_readfirstlane_b32 s20, v107
	global_load_lds_dwordx4 v[86:87], off
	v_lshl_add_u64 v[86:87], v[88:89], 0, s[8:9]
	s_mov_b32 m0, s20
	v_readfirstlane_b32 s20, v108
	global_load_lds_dwordx4 v[86:87], off
	v_lshl_add_u64 v[86:87], v[90:91], 0, s[8:9]
	s_mov_b32 m0, s20
	v_readfirstlane_b32 s20, v109
	global_load_lds_dwordx4 v[86:87], off
	v_lshl_add_u64 v[86:87], v[92:93], 0, s[8:9]
	s_mov_b32 m0, s20
	v_readfirstlane_b32 s20, v110
	global_load_lds_dwordx4 v[86:87], off
	v_lshl_add_u64 v[86:87], v[94:95], 0, s[8:9]
	s_mov_b32 m0, s20
	v_readfirstlane_b32 s20, v111
	global_load_lds_dwordx4 v[86:87], off
	v_lshl_add_u64 v[86:87], v[96:97], 0, s[8:9]
	s_mov_b32 m0, s20
	v_readfirstlane_b32 s20, v112
	global_load_lds_dwordx4 v[86:87], off
	v_lshl_add_u64 v[86:87], v[98:99], 0, s[8:9]
	s_mov_b32 m0, s20
	v_readfirstlane_b32 s20, v113
	global_load_lds_dwordx4 v[86:87], off
	v_lshl_add_u64 v[86:87], v[100:101], 0, s[8:9]
	s_mov_b32 m0, s20
	s_nop 0
	global_load_lds_dwordx4 v[86:87], off
	s_branch .LBB0_893

; template <bool DB, class AF>
; DEVI void gemm_mainloop(int tid, u16* sA, u16* sB, AF af, const u16* __restrict__ Bt, int ldb, int m0, int n0, int nk,
;                         f32x4 (&acc)[4][4]) {
;     ...
;     STAGE_(0, 0)
; #pragma unroll 1
;     for (int kt = 0; kt < nk; kt += 2) {
;       asm volatile("s_waitcnt vmcnt(0)" ::: "memory");
;       __syncthreads();
;       { const int kk = (kt + 1) * 64; STAGE_(1, kk) }
;       COMPUTE_SW_(0)
;       asm volatile("s_waitcnt vmcnt(0)" ::: "memory");
;       __syncthreads();
;       if (kt + 2 < nk) { const int kk = (kt + 2) * 64; STAGE_(0, kk) }
;       COMPUTE_SW_(1)
.LBB0_963:
	s_nop 0
	ds_read_b128 v[86:89], v121 offset:32768
	ds_read_b128 v[90:93], v121 offset:34816
	ds_read_b128 v[94:97], v121 offset:36864
	ds_read_b128 v[98:101], v121 offset:38912
	ds_read_b128 v[126:129], v122 offset:49152
	ds_read_b128 v[130:133], v122 offset:51200
	ds_read_b128 v[134:137], v122 offset:53248
	ds_read_b128 v[138:141], v122 offset:55296
	s_add_i32 s20, s20, 2
	s_setprio 1
	s_waitcnt lgkmcnt(0)
	v_mfma_f32_16x16x32_bf16 v[0:3], v[126:129], v[86:89], v[0:3]
	v_mfma_f32_16x16x32_bf16 v[4:7], v[126:129], v[90:93], v[4:7]
	v_mfma_f32_16x16x32_bf16 v[8:11], v[126:129], v[94:97], v[8:11]
	v_mfma_f32_16x16x32_bf16 v[12:15], v[126:129], v[98:101], v[12:15]
	v_mfma_f32_16x16x32_bf16 v[16:19], v[130:133], v[86:89], v[16:19]
	v_mfma_f32_16x16x32_bf16 v[20:23], v[130:133], v[90:93], v[20:23]
	v_mfma_f32_16x16x32_bf16 v[24:27], v[130:133], v[94:97], v[24:27]
	v_mfma_f32_16x16x32_bf16 v[32:35], v[134:137], v[86:89], v[32:35]
	v_mfma_f32_16x16x32_bf16 v[36:39], v[134:137], v[90:93], v[36:39]
	v_mfma_f32_16x16x32_bf16 v[48:51], v[138:141], v[86:89], v[48:51]
	v_mfma_f32_16x16x32_bf16 v[126:129], v[130:133], v[98:101], v[28:31]
	v_mfma_f32_16x16x32_bf16 v[130:133], v[134:137], v[94:97], v[40:43]
	v_mfma_f32_16x16x32_bf16 v[134:137], v[134:137], v[98:101], v[44:47]
	v_mfma_f32_16x16x32_bf16 v[86:89], v[138:141], v[90:93], v[52:55]
	v_mfma_f32_16x16x32_bf16 v[90:93], v[138:141], v[94:97], v[56:59]
	v_mfma_f32_16x16x32_bf16 v[94:97], v[138:141], v[98:101], v[60:63]
	s_setprio 0
	ds_read_b128 v[98:101], v123 offset:32768
	ds_read_b128 v[138:141], v123 offset:34816
	ds_read_b128 v[142:145], v123 offset:36864
	ds_read_b128 v[146:149], v123 offset:38912
	ds_read_b128 v[40:43], v124 offset:49152
	ds_read_b128 v[52:55], v124 offset:51200
	ds_read_b128 v[150:153], v124 offset:53248
	ds_read_b128 v[154:157], v124 offset:55296
	s_setprio 1
	s_waitcnt lgkmcnt(3)
	v_mfma_f32_16x16x32_bf16 v[60:63], v[40:43], v[98:101], v[0:3]
	v_mfma_f32_16x16x32_bf16 v[44:47], v[40:43], v[138:141], v[4:7]
	v_mfma_f32_16x16x32_bf16 v[28:31], v[40:43], v[142:145], v[8:11]
	v_mfma_f32_16x16x32_bf16 v[12:15], v[40:43], v[146:149], v[12:15]
	s_waitcnt lgkmcnt(2)
	v_mfma_f32_16x16x32_bf16 v[56:59], v[52:55], v[98:101], v[16:19]
	v_mfma_f32_16x16x32_bf16 v[40:43], v[52:55], v[138:141], v[20:23]
	v_mfma_f32_16x16x32_bf16 v[24:27], v[52:55], v[142:145], v[24:27]
	v_mfma_f32_16x16x32_bf16 v[8:11], v[52:55], v[146:149], v[126:129]
	s_waitcnt lgkmcnt(1)
	v_mfma_f32_16x16x32_bf16 v[52:55], v[150:153], v[98:101], v[32:35]
	v_mfma_f32_16x16x32_bf16 v[36:39], v[150:153], v[138:141], v[36:39]
	v_mfma_f32_16x16x32_bf16 v[20:23], v[150:153], v[142:145], v[130:133]
	v_mfma_f32_16x16x32_bf16 v[4:7], v[150:153], v[146:149], v[134:137]
	s_waitcnt lgkmcnt(0)
	v_mfma_f32_16x16x32_bf16 v[48:51], v[154:157], v[98:101], v[48:51]
	v_mfma_f32_16x16x32_bf16 v[32:35], v[154:157], v[138:141], v[86:89]
	v_mfma_f32_16x16x32_bf16 v[16:19], v[154:157], v[142:145], v[90:93]
	v_mfma_f32_16x16x32_bf16 v[0:3], v[154:157], v[146:149], v[94:97]
	s_setprio 0
	v_lshl_add_u64 v[70:71], v[70:71], 0, s[6:7]
	v_lshl_add_u64 v[72:73], v[72:73], 0, s[6:7]
	v_lshl_add_u64 v[74:75], v[74:75], 0, s[6:7]
	v_lshl_add_u64 v[76:77], v[76:77], 0, s[6:7]
	v_lshl_add_u64 v[78:79], v[78:79], 0, s[6:7]
	v_lshl_add_u64 v[80:81], v[80:81], 0, s[6:7]
	v_lshl_add_u64 v[82:83], v[82:83], 0, s[6:7]
	s_andn2_b64 vcc, exec, s[8:9]
	v_lshl_add_u64 v[84:85], v[84:85], 0, s[6:7]
	s_cbranch_vccz .LBB0_961
; template <bool DB, class AF>
; DEVI void gemm_mainloop(int tid, u16* sA, u16* sB, AF af, const u16* __restrict__ Bt, int ldb, int m0, int n0, int nk,
;                         f32x4 (&acc)[4][4]) {
;     ...
;     STAGE_(0, 0)
; #pragma unroll 1
;     for (int kt = 0; kt < nk; kt += 2) {
;       asm volatile("s_waitcnt vmcnt(0)" ::: "memory");
;       __syncthreads();
;       { const int kk = (kt + 1) * 64; STAGE_(1, kk) }
;       COMPUTE_SW_(0)
;       asm volatile("s_waitcnt vmcnt(0)" ::: "memory");
;       __syncthreads();
;       if (kt + 2 < nk) { const int kk = (kt + 2) * 64; STAGE_(0, kk) }
;       COMPUTE_SW_(1)
.LBB0_964:
	v_lshl_add_u64 v[86:87], v[78:79], 0, v[64:65]
	v_readfirstlane_b32 s8, v113
	v_lshl_add_u64 v[88:89], v[86:87], 0, s[4:5]
	s_mov_b32 m0, s8
	s_waitcnt vmcnt(0)
	s_waitcnt vmcnt(0) lgkmcnt(0)
	s_barrier
	global_load_lds_dwordx4 v[88:89], off
	v_lshl_add_u64 v[88:89], v[70:71], 0, v[64:65]
	v_readfirstlane_b32 s8, v114
	v_lshl_add_u64 v[90:91], v[88:89], 0, s[4:5]
	s_mov_b32 m0, s8
	v_readfirstlane_b32 s8, v115
	global_load_lds_dwordx4 v[90:91], off
	v_lshl_add_u64 v[90:91], v[80:81], 0, v[64:65]
	v_lshl_add_u64 v[92:93], v[90:91], 0, s[4:5]
	s_mov_b32 m0, s8
	v_readfirstlane_b32 s8, v116
	global_load_lds_dwordx4 v[92:93], off
	v_lshl_add_u64 v[92:93], v[72:73], 0, v[64:65]
	v_lshl_add_u64 v[94:95], v[92:93], 0, s[4:5]
	s_mov_b32 m0, s8
	v_readfirstlane_b32 s8, v117
	global_load_lds_dwordx4 v[94:95], off
	v_lshl_add_u64 v[94:95], v[82:83], 0, v[64:65]
	v_lshl_add_u64 v[96:97], v[94:95], 0, s[4:5]
	s_mov_b32 m0, s8
	v_readfirstlane_b32 s8, v118
	global_load_lds_dwordx4 v[96:97], off
	v_lshl_add_u64 v[96:97], v[74:75], 0, v[64:65]
	v_lshl_add_u64 v[98:99], v[96:97], 0, s[4:5]
	s_mov_b32 m0, s8
	v_readfirstlane_b32 s8, v119
	global_load_lds_dwordx4 v[98:99], off
	v_lshl_add_u64 v[98:99], v[84:85], 0, v[64:65]
	v_lshl_add_u64 v[100:101], v[98:99], 0, s[4:5]
	s_mov_b32 m0, s8
	v_readfirstlane_b32 s8, v120
	global_load_lds_dwordx4 v[100:101], off
	v_lshl_add_u64 v[100:101], v[76:77], 0, v[64:65]
	v_lshl_add_u64 v[126:127], v[100:101], 0, s[4:5]
	s_mov_b32 m0, s8
	s_nop 0
	global_load_lds_dwordx4 v[126:127], off
	s_nop 0
	ds_read_b128 v[126:129], v121
	ds_read_b128 v[130:133], v121 offset:2048
	ds_read_b128 v[134:137], v121 offset:4096
	ds_read_b128 v[138:141], v121 offset:6144
	ds_read_b128 v[142:145], v122 offset:16384
	ds_read_b128 v[146:149], v122 offset:18432
	ds_read_b128 v[150:153], v122 offset:20480
	ds_read_b128 v[154:157], v122 offset:22528
	s_setprio 1
	s_waitcnt lgkmcnt(0)
	v_mfma_f32_16x16x32_bf16 v[60:63], v[142:145], v[126:129], v[60:63]
	v_mfma_f32_16x16x32_bf16 v[44:47], v[142:145], v[130:133], v[44:47]
	v_mfma_f32_16x16x32_bf16 v[28:31], v[142:145], v[134:137], v[28:31]
	v_mfma_f32_16x16x32_bf16 v[12:15], v[142:145], v[138:141], v[12:15]
	v_mfma_f32_16x16x32_bf16 v[56:59], v[146:149], v[126:129], v[56:59]
	v_mfma_f32_16x16x32_bf16 v[40:43], v[146:149], v[130:133], v[40:43]
	v_mfma_f32_16x16x32_bf16 v[24:27], v[146:149], v[134:137], v[24:27]
	v_mfma_f32_16x16x32_bf16 v[52:55], v[150:153], v[126:129], v[52:55]
	v_mfma_f32_16x16x32_bf16 v[36:39], v[150:153], v[130:133], v[36:39]
	v_mfma_f32_16x16x32_bf16 v[48:51], v[154:157], v[126:129], v[48:51]
	v_mfma_f32_16x16x32_bf16 v[142:145], v[146:149], v[138:141], v[8:11]
	v_mfma_f32_16x16x32_bf16 v[146:149], v[150:153], v[134:137], v[20:23]
	v_mfma_f32_16x16x32_bf16 v[150:153], v[150:153], v[138:141], v[4:7]
	v_mfma_f32_16x16x32_bf16 v[126:129], v[154:157], v[130:133], v[32:35]
	v_mfma_f32_16x16x32_bf16 v[130:133], v[154:157], v[134:137], v[16:19]
	v_mfma_f32_16x16x32_bf16 v[134:137], v[154:157], v[138:141], v[0:3]
	s_setprio 0
	ds_read_b128 v[138:141], v123
	ds_read_b128 v[154:157], v123 offset:2048
	ds_read_b128 v[158:161], v123 offset:4096
	ds_read_b128 v[162:165], v123 offset:6144
	ds_read_b128 v[16:19], v124 offset:16384
	ds_read_b128 v[32:35], v124 offset:18432
	ds_read_b128 v[166:169], v124 offset:20480
	ds_read_b128 v[170:173], v124 offset:22528
	s_setprio 1
	s_waitcnt lgkmcnt(3)
	v_mfma_f32_16x16x32_bf16 v[0:3], v[16:19], v[138:141], v[60:63]
	v_mfma_f32_16x16x32_bf16 v[4:7], v[16:19], v[154:157], v[44:47]
	v_mfma_f32_16x16x32_bf16 v[8:11], v[16:19], v[158:161], v[28:31]
	v_mfma_f32_16x16x32_bf16 v[12:15], v[16:19], v[162:165], v[12:15]
	s_waitcnt lgkmcnt(2)
	v_mfma_f32_16x16x32_bf16 v[16:19], v[32:35], v[138:141], v[56:59]
	v_mfma_f32_16x16x32_bf16 v[20:23], v[32:35], v[154:157], v[40:43]
	v_mfma_f32_16x16x32_bf16 v[24:27], v[32:35], v[158:161], v[24:27]
	v_mfma_f32_16x16x32_bf16 v[28:31], v[32:35], v[162:165], v[142:145]
	s_waitcnt lgkmcnt(1)
	v_mfma_f32_16x16x32_bf16 v[32:35], v[166:169], v[138:141], v[52:55]
	v_mfma_f32_16x16x32_bf16 v[36:39], v[166:169], v[154:157], v[36:39]
	v_mfma_f32_16x16x32_bf16 v[40:43], v[166:169], v[158:161], v[146:149]
	v_mfma_f32_16x16x32_bf16 v[44:47], v[166:169], v[162:165], v[150:153]
	s_waitcnt lgkmcnt(0)
	v_mfma_f32_16x16x32_bf16 v[48:51], v[170:173], v[138:141], v[48:51]
	v_mfma_f32_16x16x32_bf16 v[52:55], v[170:173], v[154:157], v[126:129]
	v_mfma_f32_16x16x32_bf16 v[56:59], v[170:173], v[158:161], v[130:133]
	v_mfma_f32_16x16x32_bf16 v[60:63], v[170:173], v[162:165], v[134:137]
	s_setprio 0
	s_waitcnt vmcnt(0)
	s_cmp_gt_u32 s20, 13
	s_cselect_b64 s[8:9], -1, 0
	s_and_b64 vcc, exec, s[8:9]
	s_barrier
	s_cbranch_vccnz .LBB0_963
	v_readfirstlane_b32 s21, v105
	v_lshl_add_u64 v[86:87], v[86:87], 0, s[6:7]
	s_mov_b32 m0, s21
	v_readfirstlane_b32 s21, v106
	global_load_lds_dwordx4 v[86:87], off
	v_lshl_add_u64 v[86:87], v[88:89], 0, s[6:7]
	s_mov_b32 m0, s21
	v_readfirstlane_b32 s21, v107
	global_load_lds_dwordx4 v[86:87], off
	v_lshl_add_u64 v[86:87], v[90:91], 0, s[6:7]
	s_mov_b32 m0, s21
	v_readfirstlane_b32 s21, v108
	global_load_lds_dwordx4 v[86:87], off
	v_lshl_add_u64 v[86:87], v[92:93], 0, s[6:7]
	s_mov_b32 m0, s21
	v_readfirstlane_b32 s21, v109
	global_load_lds_dwordx4 v[86:87], off
	v_lshl_add_u64 v[86:87], v[94:95], 0, s[6:7]
	s_mov_b32 m0, s21
	v_readfirstlane_b32 s21, v110
	global_load_lds_dwordx4 v[86:87], off
	v_lshl_add_u64 v[86:87], v[96:97], 0, s[6:7]
	s_mov_b32 m0, s21
	v_readfirstlane_b32 s21, v111
	global_load_lds_dwordx4 v[86:87], off
	v_lshl_add_u64 v[86:87], v[98:99], 0, s[6:7]
	s_mov_b32 m0, s21
	v_readfirstlane_b32 s21, v112
	global_load_lds_dwordx4 v[86:87], off
	v_lshl_add_u64 v[86:87], v[100:101], 0, s[6:7]
	s_mov_b32 m0, s21
	s_nop 0
	global_load_lds_dwordx4 v[86:87], off
	s_branch .LBB0_963

; template <bool DB, class AF>
; DEVI void gemm_mainloop(int tid, u16* sA, u16* sB, AF af, const u16* __restrict__ Bt, int ldb, int m0, int n0, int nk,
;                         f32x4 (&acc)[4][4]) {
;     ...
;     STAGE_(0, 0)
; #pragma unroll 1
;     for (int kt = 0; kt < nk; kt += 2) {
;       asm volatile("s_waitcnt vmcnt(0)" ::: "memory");
;       __syncthreads();
;       { const int kk = (kt + 1) * 64; STAGE_(1, kk) }
;       COMPUTE_SW_(0)
;       asm volatile("s_waitcnt vmcnt(0)" ::: "memory");
;       __syncthreads();
;       if (kt + 2 < nk) { const int kk = (kt + 2) * 64; STAGE_(0, kk) }
;       COMPUTE_SW_(1)
.LBB0_1160:
	s_nop 0
	ds_read_b128 v[86:89], v121 offset:32768
	ds_read_b128 v[90:93], v121 offset:34816
	ds_read_b128 v[94:97], v121 offset:36864
	ds_read_b128 v[98:101], v121 offset:38912
	ds_read_b128 v[126:129], v122 offset:49152
	ds_read_b128 v[130:133], v122 offset:51200
	ds_read_b128 v[134:137], v122 offset:53248
	ds_read_b128 v[138:141], v122 offset:55296
	s_add_i32 s21, s21, 2
	s_setprio 1
	s_waitcnt lgkmcnt(0)
	v_mfma_f32_16x16x32_bf16 v[0:3], v[126:129], v[86:89], v[0:3]
	v_mfma_f32_16x16x32_bf16 v[4:7], v[126:129], v[90:93], v[4:7]
	v_mfma_f32_16x16x32_bf16 v[8:11], v[126:129], v[94:97], v[8:11]
	v_mfma_f32_16x16x32_bf16 v[12:15], v[126:129], v[98:101], v[12:15]
	v_mfma_f32_16x16x32_bf16 v[16:19], v[130:133], v[86:89], v[16:19]
	v_mfma_f32_16x16x32_bf16 v[20:23], v[130:133], v[90:93], v[20:23]
	v_mfma_f32_16x16x32_bf16 v[24:27], v[130:133], v[94:97], v[24:27]
	v_mfma_f32_16x16x32_bf16 v[32:35], v[134:137], v[86:89], v[32:35]
	v_mfma_f32_16x16x32_bf16 v[36:39], v[134:137], v[90:93], v[36:39]
	v_mfma_f32_16x16x32_bf16 v[48:51], v[138:141], v[86:89], v[48:51]
	v_mfma_f32_16x16x32_bf16 v[126:129], v[130:133], v[98:101], v[28:31]
	v_mfma_f32_16x16x32_bf16 v[130:133], v[134:137], v[94:97], v[40:43]
	v_mfma_f32_16x16x32_bf16 v[134:137], v[134:137], v[98:101], v[44:47]
	v_mfma_f32_16x16x32_bf16 v[86:89], v[138:141], v[90:93], v[52:55]
	v_mfma_f32_16x16x32_bf16 v[90:93], v[138:141], v[94:97], v[56:59]
	v_mfma_f32_16x16x32_bf16 v[94:97], v[138:141], v[98:101], v[60:63]
	s_setprio 0
	ds_read_b128 v[98:101], v123 offset:32768
	ds_read_b128 v[138:141], v123 offset:34816
	ds_read_b128 v[142:145], v123 offset:36864
	ds_read_b128 v[146:149], v123 offset:38912
	ds_read_b128 v[40:43], v124 offset:49152
	ds_read_b128 v[52:55], v124 offset:51200
	ds_read_b128 v[150:153], v124 offset:53248
	ds_read_b128 v[154:157], v124 offset:55296
	s_setprio 1
	s_waitcnt lgkmcnt(3)
	v_mfma_f32_16x16x32_bf16 v[60:63], v[40:43], v[98:101], v[0:3]
	v_mfma_f32_16x16x32_bf16 v[44:47], v[40:43], v[138:141], v[4:7]
	v_mfma_f32_16x16x32_bf16 v[28:31], v[40:43], v[142:145], v[8:11]
	v_mfma_f32_16x16x32_bf16 v[12:15], v[40:43], v[146:149], v[12:15]
	s_waitcnt lgkmcnt(2)
	v_mfma_f32_16x16x32_bf16 v[56:59], v[52:55], v[98:101], v[16:19]
	v_mfma_f32_16x16x32_bf16 v[40:43], v[52:55], v[138:141], v[20:23]
	v_mfma_f32_16x16x32_bf16 v[24:27], v[52:55], v[142:145], v[24:27]
	v_mfma_f32_16x16x32_bf16 v[8:11], v[52:55], v[146:149], v[126:129]
	s_waitcnt lgkmcnt(1)
	v_mfma_f32_16x16x32_bf16 v[52:55], v[150:153], v[98:101], v[32:35]
	v_mfma_f32_16x16x32_bf16 v[36:39], v[150:153], v[138:141], v[36:39]
	v_mfma_f32_16x16x32_bf16 v[20:23], v[150:153], v[142:145], v[130:133]
	v_mfma_f32_16x16x32_bf16 v[4:7], v[150:153], v[146:149], v[134:137]
	s_waitcnt lgkmcnt(0)
	v_mfma_f32_16x16x32_bf16 v[48:51], v[154:157], v[98:101], v[48:51]
	v_mfma_f32_16x16x32_bf16 v[32:35], v[154:157], v[138:141], v[86:89]
	v_mfma_f32_16x16x32_bf16 v[16:19], v[154:157], v[142:145], v[90:93]
	v_mfma_f32_16x16x32_bf16 v[0:3], v[154:157], v[146:149], v[94:97]
	s_setprio 0
	v_lshl_add_u64 v[70:71], v[70:71], 0, s[6:7]
	v_lshl_add_u64 v[72:73], v[72:73], 0, s[6:7]
	v_lshl_add_u64 v[74:75], v[74:75], 0, s[6:7]
	v_lshl_add_u64 v[76:77], v[76:77], 0, s[6:7]
	v_lshl_add_u64 v[78:79], v[78:79], 0, s[6:7]
	v_lshl_add_u64 v[80:81], v[80:81], 0, s[6:7]
	v_lshl_add_u64 v[82:83], v[82:83], 0, s[6:7]
	s_andn2_b64 vcc, exec, s[8:9]
	v_lshl_add_u64 v[84:85], v[84:85], 0, s[6:7]
	s_cbranch_vccz .LBB0_1158
; template <bool DB, class AF>
; DEVI void gemm_mainloop(int tid, u16* sA, u16* sB, AF af, const u16* __restrict__ Bt, int ldb, int m0, int n0, int nk,
;                         f32x4 (&acc)[4][4]) {
;     ...
;     STAGE_(0, 0)
; #pragma unroll 1
;     for (int kt = 0; kt < nk; kt += 2) {
;       asm volatile("s_waitcnt vmcnt(0)" ::: "memory");
;       __syncthreads();
;       { const int kk = (kt + 1) * 64; STAGE_(1, kk) }
;       COMPUTE_SW_(0)
;       asm volatile("s_waitcnt vmcnt(0)" ::: "memory");
;       __syncthreads();
;       if (kt + 2 < nk) { const int kk = (kt + 2) * 64; STAGE_(0, kk) }
;       COMPUTE_SW_(1)
.LBB0_1161:
	v_lshl_add_u64 v[86:87], v[78:79], 0, v[64:65]
	v_readfirstlane_b32 s8, v113
	v_lshl_add_u64 v[88:89], v[86:87], 0, s[4:5]
	s_mov_b32 m0, s8
	s_waitcnt vmcnt(0)
	s_waitcnt vmcnt(0) lgkmcnt(0)
	s_barrier
	global_load_lds_dwordx4 v[88:89], off
	v_lshl_add_u64 v[88:89], v[70:71], 0, v[64:65]
	v_readfirstlane_b32 s8, v114
	v_lshl_add_u64 v[90:91], v[88:89], 0, s[4:5]
	s_mov_b32 m0, s8
	v_readfirstlane_b32 s8, v115
	global_load_lds_dwordx4 v[90:91], off
	v_lshl_add_u64 v[90:91], v[80:81], 0, v[64:65]
	v_lshl_add_u64 v[92:93], v[90:91], 0, s[4:5]
	s_mov_b32 m0, s8
	v_readfirstlane_b32 s8, v116
	global_load_lds_dwordx4 v[92:93], off
	v_lshl_add_u64 v[92:93], v[72:73], 0, v[64:65]
	v_lshl_add_u64 v[94:95], v[92:93], 0, s[4:5]
	s_mov_b32 m0, s8
	v_readfirstlane_b32 s8, v117
	global_load_lds_dwordx4 v[94:95], off
	v_lshl_add_u64 v[94:95], v[82:83], 0, v[64:65]
	v_lshl_add_u64 v[96:97], v[94:95], 0, s[4:5]
	s_mov_b32 m0, s8
	v_readfirstlane_b32 s8, v118
	global_load_lds_dwordx4 v[96:97], off
	v_lshl_add_u64 v[96:97], v[74:75], 0, v[64:65]
	v_lshl_add_u64 v[98:99], v[96:97], 0, s[4:5]
	s_mov_b32 m0, s8
	v_readfirstlane_b32 s8, v119
	global_load_lds_dwordx4 v[98:99], off
	v_lshl_add_u64 v[98:99], v[84:85], 0, v[64:65]
	v_lshl_add_u64 v[100:101], v[98:99], 0, s[4:5]
	s_mov_b32 m0, s8
	v_readfirstlane_b32 s8, v120
	global_load_lds_dwordx4 v[100:101], off
	v_lshl_add_u64 v[100:101], v[76:77], 0, v[64:65]
	v_lshl_add_u64 v[126:127], v[100:101], 0, s[4:5]
	s_mov_b32 m0, s8
	s_nop 0
	global_load_lds_dwordx4 v[126:127], off
	s_nop 0
	ds_read_b128 v[126:129], v121
	ds_read_b128 v[130:133], v121 offset:2048
	ds_read_b128 v[134:137], v121 offset:4096
	ds_read_b128 v[138:141], v121 offset:6144
	ds_read_b128 v[142:145], v122 offset:16384
	ds_read_b128 v[146:149], v122 offset:18432
	ds_read_b128 v[150:153], v122 offset:20480
	ds_read_b128 v[154:157], v122 offset:22528
	s_setprio 1
	s_waitcnt lgkmcnt(0)
	v_mfma_f32_16x16x32_bf16 v[60:63], v[142:145], v[126:129], v[60:63]
	v_mfma_f32_16x16x32_bf16 v[44:47], v[142:145], v[130:133], v[44:47]
	v_mfma_f32_16x16x32_bf16 v[28:31], v[142:145], v[134:137], v[28:31]
	v_mfma_f32_16x16x32_bf16 v[12:15], v[142:145], v[138:141], v[12:15]
	v_mfma_f32_16x16x32_bf16 v[56:59], v[146:149], v[126:129], v[56:59]
	v_mfma_f32_16x16x32_bf16 v[40:43], v[146:149], v[130:133], v[40:43]
	v_mfma_f32_16x16x32_bf16 v[24:27], v[146:149], v[134:137], v[24:27]
	v_mfma_f32_16x16x32_bf16 v[52:55], v[150:153], v[126:129], v[52:55]
	v_mfma_f32_16x16x32_bf16 v[36:39], v[150:153], v[130:133], v[36:39]
	v_mfma_f32_16x16x32_bf16 v[48:51], v[154:157], v[126:129], v[48:51]
	v_mfma_f32_16x16x32_bf16 v[142:145], v[146:149], v[138:141], v[8:11]
	v_mfma_f32_16x16x32_bf16 v[146:149], v[150:153], v[134:137], v[20:23]
	v_mfma_f32_16x16x32_bf16 v[150:153], v[150:153], v[138:141], v[4:7]
	v_mfma_f32_16x16x32_bf16 v[126:129], v[154:157], v[130:133], v[32:35]
	v_mfma_f32_16x16x32_bf16 v[130:133], v[154:157], v[134:137], v[16:19]
	v_mfma_f32_16x16x32_bf16 v[134:137], v[154:157], v[138:141], v[0:3]
	s_setprio 0
	ds_read_b128 v[138:141], v123
	ds_read_b128 v[154:157], v123 offset:2048
	ds_read_b128 v[158:161], v123 offset:4096
	ds_read_b128 v[162:165], v123 offset:6144
	ds_read_b128 v[16:19], v124 offset:16384
	ds_read_b128 v[32:35], v124 offset:18432
	ds_read_b128 v[166:169], v124 offset:20480
	ds_read_b128 v[170:173], v124 offset:22528
	s_setprio 1
	s_waitcnt lgkmcnt(3)
	v_mfma_f32_16x16x32_bf16 v[0:3], v[16:19], v[138:141], v[60:63]
	v_mfma_f32_16x16x32_bf16 v[4:7], v[16:19], v[154:157], v[44:47]
	v_mfma_f32_16x16x32_bf16 v[8:11], v[16:19], v[158:161], v[28:31]
	v_mfma_f32_16x16x32_bf16 v[12:15], v[16:19], v[162:165], v[12:15]
	s_waitcnt lgkmcnt(2)
	v_mfma_f32_16x16x32_bf16 v[16:19], v[32:35], v[138:141], v[56:59]
	v_mfma_f32_16x16x32_bf16 v[20:23], v[32:35], v[154:157], v[40:43]
	v_mfma_f32_16x16x32_bf16 v[24:27], v[32:35], v[158:161], v[24:27]
	v_mfma_f32_16x16x32_bf16 v[28:31], v[32:35], v[162:165], v[142:145]
	s_waitcnt lgkmcnt(1)
	v_mfma_f32_16x16x32_bf16 v[32:35], v[166:169], v[138:141], v[52:55]
	v_mfma_f32_16x16x32_bf16 v[36:39], v[166:169], v[154:157], v[36:39]
	v_mfma_f32_16x16x32_bf16 v[40:43], v[166:169], v[158:161], v[146:149]
	v_mfma_f32_16x16x32_bf16 v[44:47], v[166:169], v[162:165], v[150:153]
	s_waitcnt lgkmcnt(0)
	v_mfma_f32_16x16x32_bf16 v[48:51], v[170:173], v[138:141], v[48:51]
	v_mfma_f32_16x16x32_bf16 v[52:55], v[170:173], v[154:157], v[126:129]
	v_mfma_f32_16x16x32_bf16 v[56:59], v[170:173], v[158:161], v[130:133]
	v_mfma_f32_16x16x32_bf16 v[60:63], v[170:173], v[162:165], v[134:137]
	s_setprio 0
	s_waitcnt vmcnt(0)
	s_cmp_gt_u32 s21, 13
	s_cselect_b64 s[8:9], -1, 0
	s_and_b64 vcc, exec, s[8:9]
	s_barrier
	s_cbranch_vccnz .LBB0_1160
	v_readfirstlane_b32 s22, v105
	v_lshl_add_u64 v[86:87], v[86:87], 0, s[6:7]
	s_mov_b32 m0, s22
	v_readfirstlane_b32 s22, v106
	global_load_lds_dwordx4 v[86:87], off
	v_lshl_add_u64 v[86:87], v[88:89], 0, s[6:7]
	s_mov_b32 m0, s22
	v_readfirstlane_b32 s22, v107
	global_load_lds_dwordx4 v[86:87], off
	v_lshl_add_u64 v[86:87], v[90:91], 0, s[6:7]
	s_mov_b32 m0, s22
	v_readfirstlane_b32 s22, v108
	global_load_lds_dwordx4 v[86:87], off
	v_lshl_add_u64 v[86:87], v[92:93], 0, s[6:7]
	s_mov_b32 m0, s22
	v_readfirstlane_b32 s22, v109
	global_load_lds_dwordx4 v[86:87], off
	v_lshl_add_u64 v[86:87], v[94:95], 0, s[6:7]
	s_mov_b32 m0, s22
	v_readfirstlane_b32 s22, v110
	global_load_lds_dwordx4 v[86:87], off
	v_lshl_add_u64 v[86:87], v[96:97], 0, s[6:7]
	s_mov_b32 m0, s22
	v_readfirstlane_b32 s22, v111
	global_load_lds_dwordx4 v[86:87], off
	v_lshl_add_u64 v[86:87], v[98:99], 0, s[6:7]
	s_mov_b32 m0, s22
	v_readfirstlane_b32 s22, v112
	global_load_lds_dwordx4 v[86:87], off
	v_lshl_add_u64 v[86:87], v[100:101], 0, s[6:7]
	s_mov_b32 m0, s22
	s_nop 0
	global_load_lds_dwordx4 v[86:87], off
	s_branch .LBB0_1160
